# grid barrier: all workgroups poll the cumulative top counter (no TOPGEN / per-XCD generation relay), leader adds without return
# speedup vs baseline: 1.0004x; 1.0004x over previous
; __device__ __forceinline__ unsigned xb_ld(unsigned* p)              { return __hip_atomic_load(p, __ATOMIC_RELAXED, __HIP_MEMORY_SCOPE_AGENT); }
; __device__ __forceinline__ unsigned xb_add(unsigned* p, unsigned v) { return __hip_atomic_fetch_add(p, v, __ATOMIC_RELAXED, __HIP_MEMORY_SCOPE_AGENT); }
; #define XB_SPIN(cond, bar) do { unsigned _sp = 0; while (cond) { __builtin_amdgcn_s_sleep(1); \
;     if ((++_sp & 255u) == 0u) { if (xb_ld(&(bar)[XB_TMO])) break; if (_sp > XB_SPIN_CAP) { atomicAdd(&(bar)[XB_TMO], 1u); break; } } } } while (0)
; __device__ __forceinline__ void xcd_barrier(const XcdBarrier& b) {
;     ...
;     if (threadIdx.x == 0) {
;         unsigned* bar = b.bar;
;         __builtin_amdgcn_s_waitcnt(0);
;         unsigned nloc = b.st[0], nx = b.st[1];
;         if (nloc == 0u) { xcd_barrier_complete(bar, b.x, nloc, nx); b.st[0] = nloc; b.st[1] = nx; }
;         const unsigned old = xb_add(&bar[XB_XSUB(b.x)], 1u);
;         const unsigned gen = old / nloc;
;         if (old + 1u == (gen + 1u) * nloc) {
;             __builtin_amdgcn_fence(__ATOMIC_RELEASE, "agent");
;             asm volatile("s_waitcnt vmcnt(0)" ::: "memory");
;             const unsigned og = xb_add(&bar[XB_TOP], 1u);
;             const unsigned tg = og / nx;
;             if (og + 1u == (tg + 1u) * nx) xb_add(&bar[XB_TOPGEN], 1u);
;             else XB_SPIN(xb_ld(&bar[XB_TOPGEN]) == tg, bar);
;             __builtin_amdgcn_fence(__ATOMIC_ACQUIRE, "agent");
;             xb_add(&bar[XB_XGEN(b.x)], 1u);
;             asm volatile("s_waitcnt vmcnt(0)" ::: "memory");
;         } else {
;             XB_SPIN(xb_ld(&bar[XB_XGEN(b.x)]) == gen, bar);
;             __builtin_amdgcn_fence(__ATOMIC_ACQUIRE, "agent");
;             asm volatile("s_waitcnt vmcnt(0)" ::: "memory");
;         }
.LBB0_143:
	v_readlane_b32 s3, v254, 5
	s_lshl_b32 s3, s3, 8
	v_readlane_b32 s6, v254, 3
	v_readlane_b32 s7, v254, 4
	s_add_u32 s6, s6, s3
	s_addc_u32 s7, s7, 0
	v_mov_b32_e32 v3, 0x1000
	v_mov_b32_e32 v4, 1
	v_mov_b32_e32 v1, 0
	s_nop 0
	global_atomic_add v3, v3, v4, s[6:7] offset:1024 sc0
	s_waitcnt lgkmcnt(0)
	v_cvt_f32_u32_e32 v4, v2
	s_waitcnt vmcnt(0)
	v_readfirstlane_b32 s3, v3
	v_sub_u32_e32 v3, 0, v2
	v_rcp_iflag_f32_e32 v4, v4
	v_add_u32_e32 v5, s3, v1
	v_mul_f32_e32 v4, 0x4f7ffffe, v4
	v_cvt_u32_f32_e32 v4, v4
	v_mul_lo_u32 v1, v3, v4
	v_mul_hi_u32 v1, v4, v1
	v_add_u32_e32 v1, v4, v1
	v_mul_hi_u32 v1, v5, v1
	v_mul_lo_u32 v3, v1, v2
	v_sub_u32_e32 v3, v5, v3
	v_add_u32_e32 v4, 1, v1
	v_cmp_ge_u32_e32 vcc, v3, v2
	s_nop 1
	v_cndmask_b32_e32 v1, v1, v4, vcc
	v_sub_u32_e32 v4, v3, v2
	v_cndmask_b32_e32 v3, v3, v4, vcc
	v_add_u32_e32 v4, 1, v1
	v_cmp_ge_u32_e32 vcc, v3, v2
	v_add_u32_e32 v3, 1, v5
	s_nop 0
	v_cndmask_b32_e32 v1, v1, v4, vcc
	v_add_u32_e32 v1, 1, v1
	v_mul_lo_u32 v2, v2, v1
	v_mul_lo_u32 v0, v0, v1
	v_cmp_ne_u32_e32 vcc, v3, v2
	v_mov_b32_e32 v3, 0x1ffff000
	s_cbranch_vccnz .Lfb_poll_0
	buffer_wbl2 sc1
	s_waitcnt vmcnt(0)
	v_mov_b32_e32 v4, 1
	global_atomic_add v3, v4, s[50:51] offset:1024
.Lfb_poll_0:
	s_mov_b32 s3, 0
.Lfb_spin_0:
	global_load_dword v1, v3, s[50:51] offset:1024 sc1
	s_waitcnt vmcnt(0)
	v_cmp_ge_u32_e32 vcc, v1, v0
	s_cbranch_vccnz .Lfb_done_0
	s_sleep 1
	s_add_i32 s3, s3, 1
	s_and_b32 vcc_lo, s3, 0xff
	s_cmp_lg_u32 vcc_lo, 0
	s_cbranch_scc1 .Lfb_spin_0
	v_mov_b32_e32 v4, 0x1fffc000
	global_load_dword v1, v4, s[50:51] offset:512 sc1
	s_waitcnt vmcnt(0)
	v_cmp_ne_u32_e32 vcc, 0, v1
	s_cbranch_vccnz .Lfb_done_0
	s_cmp_lt_u32 s3, 0x4000
	s_cbranch_scc1 .Lfb_spin_0
	v_mov_b32_e32 v1, 1
	global_atomic_add v4, v1, s[50:51] offset:512
.Lfb_done_0:
	s_waitcnt vmcnt(0)
	buffer_inv sc1
	s_waitcnt vmcnt(0)

; __device__ __forceinline__ unsigned xb_ld(unsigned* p)              { return __hip_atomic_load(p, __ATOMIC_RELAXED, __HIP_MEMORY_SCOPE_AGENT); }
; __device__ __forceinline__ unsigned xb_add(unsigned* p, unsigned v) { return __hip_atomic_fetch_add(p, v, __ATOMIC_RELAXED, __HIP_MEMORY_SCOPE_AGENT); }
; #define XB_SPIN(cond, bar) do { unsigned _sp = 0; while (cond) { __builtin_amdgcn_s_sleep(1); \
;     if ((++_sp & 255u) == 0u) { if (xb_ld(&(bar)[XB_TMO])) break; if (_sp > XB_SPIN_CAP) { atomicAdd(&(bar)[XB_TMO], 1u); break; } } } } while (0)
; __device__ __forceinline__ void xcd_barrier(const XcdBarrier& b) {
;     ...
;     if (threadIdx.x == 0) {
;         unsigned* bar = b.bar;
;         __builtin_amdgcn_s_waitcnt(0);
;         unsigned nloc = b.st[0], nx = b.st[1];
;         if (nloc == 0u) { xcd_barrier_complete(bar, b.x, nloc, nx); b.st[0] = nloc; b.st[1] = nx; }
;         const unsigned old = xb_add(&bar[XB_XSUB(b.x)], 1u);
;         const unsigned gen = old / nloc;
;         if (old + 1u == (gen + 1u) * nloc) {
;             __builtin_amdgcn_fence(__ATOMIC_RELEASE, "agent");
;             asm volatile("s_waitcnt vmcnt(0)" ::: "memory");
;             const unsigned og = xb_add(&bar[XB_TOP], 1u);
;             const unsigned tg = og / nx;
;             if (og + 1u == (tg + 1u) * nx) xb_add(&bar[XB_TOPGEN], 1u);
;             else XB_SPIN(xb_ld(&bar[XB_TOPGEN]) == tg, bar);
;             __builtin_amdgcn_fence(__ATOMIC_ACQUIRE, "agent");
;             xb_add(&bar[XB_XGEN(b.x)], 1u);
;             asm volatile("s_waitcnt vmcnt(0)" ::: "memory");
;         } else {
;             XB_SPIN(xb_ld(&bar[XB_XGEN(b.x)]) == gen, bar);
;             __builtin_amdgcn_fence(__ATOMIC_ACQUIRE, "agent");
;             asm volatile("s_waitcnt vmcnt(0)" ::: "memory");
;         }
.LBB0_1093:
	v_readlane_b32 s8, v254, 5
	s_lshl_b32 s8, s8, 8
	v_readlane_b32 s6, v254, 3
	v_readlane_b32 s7, v254, 4
	s_add_u32 s6, s6, s8
	s_addc_u32 s7, s7, 0
	v_mov_b32_e32 v3, 0x1000
	v_mov_b32_e32 v4, 1
	v_mov_b32_e32 v1, 0
	s_nop 0
	global_atomic_add v3, v3, v4, s[6:7] offset:1024 sc0
	s_waitcnt lgkmcnt(0)
	v_cvt_f32_u32_e32 v4, v2
	s_waitcnt vmcnt(0)
	v_readfirstlane_b32 s8, v3
	v_sub_u32_e32 v3, 0, v2
	v_rcp_iflag_f32_e32 v4, v4
	v_add_u32_e32 v5, s8, v1
	v_mul_f32_e32 v4, 0x4f7ffffe, v4
	v_cvt_u32_f32_e32 v4, v4
	v_mul_lo_u32 v1, v3, v4
	v_mul_hi_u32 v1, v4, v1
	v_add_u32_e32 v1, v4, v1
	v_mul_hi_u32 v1, v5, v1
	v_mul_lo_u32 v3, v1, v2
	v_sub_u32_e32 v3, v5, v3
	v_add_u32_e32 v4, 1, v1
	v_cmp_ge_u32_e32 vcc, v3, v2
	s_nop 1
	v_cndmask_b32_e32 v1, v1, v4, vcc
	v_sub_u32_e32 v4, v3, v2
	v_cndmask_b32_e32 v3, v3, v4, vcc
	v_add_u32_e32 v4, 1, v1
	v_cmp_ge_u32_e32 vcc, v3, v2
	v_add_u32_e32 v3, 1, v5
	s_nop 0
	v_cndmask_b32_e32 v1, v1, v4, vcc
	v_add_u32_e32 v1, 1, v1
	v_mul_lo_u32 v2, v2, v1
	v_mul_lo_u32 v0, v0, v1
	v_cmp_ne_u32_e32 vcc, v3, v2
	v_mov_b32_e32 v3, 0x1ffff000
	s_cbranch_vccnz .Lfb_poll_8
	buffer_wbl2 sc1
	s_waitcnt vmcnt(0)
	v_mov_b32_e32 v4, 1
	global_atomic_add v3, v4, s[50:51] offset:1024
.Lfb_poll_8:
	s_mov_b32 s8, 0
.Lfb_spin_8:
	global_load_dword v1, v3, s[50:51] offset:1024 sc1
	s_waitcnt vmcnt(0)
	v_cmp_ge_u32_e32 vcc, v1, v0
	s_cbranch_vccnz .Lfb_done_8
	s_sleep 1
	s_add_i32 s8, s8, 1
	s_and_b32 vcc_lo, s8, 0xff
	s_cmp_lg_u32 vcc_lo, 0
	s_cbranch_scc1 .Lfb_spin_8
	v_mov_b32_e32 v4, 0x1fffc000
	global_load_dword v1, v4, s[50:51] offset:512 sc1
	s_waitcnt vmcnt(0)
	v_cmp_ne_u32_e32 vcc, 0, v1
	s_cbranch_vccnz .Lfb_done_8
	s_cmp_lt_u32 s8, 0x4000
	s_cbranch_scc1 .Lfb_spin_8
	v_mov_b32_e32 v1, 1
	global_atomic_add v4, v1, s[50:51] offset:512

; __device__ __forceinline__ unsigned xb_ld(unsigned* p)              { return __hip_atomic_load(p, __ATOMIC_RELAXED, __HIP_MEMORY_SCOPE_AGENT); }
; __device__ __forceinline__ unsigned xb_add(unsigned* p, unsigned v) { return __hip_atomic_fetch_add(p, v, __ATOMIC_RELAXED, __HIP_MEMORY_SCOPE_AGENT); }
; #define XB_SPIN(cond, bar) do { unsigned _sp = 0; while (cond) { __builtin_amdgcn_s_sleep(1); \
;     if ((++_sp & 255u) == 0u) { if (xb_ld(&(bar)[XB_TMO])) break; if (_sp > XB_SPIN_CAP) { atomicAdd(&(bar)[XB_TMO], 1u); break; } } } } while (0)
; __device__ __forceinline__ void xcd_barrier(const XcdBarrier& b) {
;     ...
;         if (nloc == 0u) { xcd_barrier_complete(bar, b.x, nloc, nx); b.st[0] = nloc; b.st[1] = nx; }
;         const unsigned old = xb_add(&bar[XB_XSUB(b.x)], 1u);
;         const unsigned gen = old / nloc;
;         if (old + 1u == (gen + 1u) * nloc) {
;             __builtin_amdgcn_fence(__ATOMIC_RELEASE, "agent");
;             asm volatile("s_waitcnt vmcnt(0)" ::: "memory");
;             const unsigned og = xb_add(&bar[XB_TOP], 1u);
;             const unsigned tg = og / nx;
;             if (og + 1u == (tg + 1u) * nx) xb_add(&bar[XB_TOPGEN], 1u);
;             else XB_SPIN(xb_ld(&bar[XB_TOPGEN]) == tg, bar);
.LBB0_1178:
	v_readlane_b32 s3, v254, 5
	s_lshl_b32 s3, s3, 8
	v_readlane_b32 s8, v254, 3
	v_readlane_b32 s9, v254, 4
	s_add_u32 s8, s8, s3
	s_addc_u32 s9, s9, 0
	v_mov_b32_e32 v3, 0x1000
	v_mov_b32_e32 v4, 1
	v_mov_b32_e32 v1, 0
	s_nop 0
	global_atomic_add v3, v3, v4, s[8:9] offset:1024 sc0
	s_waitcnt lgkmcnt(0)
	v_cvt_f32_u32_e32 v4, v2
	s_waitcnt vmcnt(0)
	v_readfirstlane_b32 s3, v3
	v_sub_u32_e32 v3, 0, v2
	v_rcp_iflag_f32_e32 v4, v4
	v_add_u32_e32 v5, s3, v1
	v_mul_f32_e32 v4, 0x4f7ffffe, v4
	v_cvt_u32_f32_e32 v4, v4
	v_mul_lo_u32 v1, v3, v4
	v_mul_hi_u32 v1, v4, v1
	v_add_u32_e32 v1, v4, v1
	v_mul_hi_u32 v1, v5, v1
	v_mul_lo_u32 v3, v1, v2
	v_sub_u32_e32 v3, v5, v3
	v_add_u32_e32 v4, 1, v1
	v_cmp_ge_u32_e32 vcc, v3, v2
	s_nop 1
	v_cndmask_b32_e32 v1, v1, v4, vcc
	v_sub_u32_e32 v4, v3, v2
	v_cndmask_b32_e32 v3, v3, v4, vcc
	v_add_u32_e32 v4, 1, v1
	v_cmp_ge_u32_e32 vcc, v3, v2
	v_add_u32_e32 v3, 1, v5
	s_nop 0
	v_cndmask_b32_e32 v1, v1, v4, vcc
	v_add_u32_e32 v1, 1, v1
	v_mul_lo_u32 v2, v2, v1
	v_mul_lo_u32 v0, v0, v1
	v_cmp_ne_u32_e32 vcc, v3, v2
	v_mov_b32_e32 v3, 0x1ffff000
	s_cbranch_vccnz .Lfb_poll_9
	buffer_wbl2 sc1
	s_waitcnt vmcnt(0)
	v_mov_b32_e32 v4, 1
	global_atomic_add v3, v4, s[50:51] offset:1024
